# attention: K/V LDS tiles double-buffered (second image at +32 KiB, base VGPRs toggled per tile), so the barrier in front of each tile's ds_writes is removed: one s_barrier per key tile instead of two
# baseline (speedup 1.0000x reference)
.LBB0_871:
	s_add_i32 s28, s28, 1
	s_cmp_ge_u32 s28, s94
	s_cselect_b64 s[54:55], -1, 0
	s_and_b64 vcc, exec, s[54:55]
	ds_write_b128 v220, v[24:27]
	ds_write_b128 v220, v[20:23] offset:9216
	s_waitcnt lgkmcnt(0)
	s_barrier
	s_cbranch_vccnz .LBB0_873
	v_add3_u32 v20, v139, s71, 48
	v_ashrrev_i32_e32 v21, 31, v20
	v_add3_u32 v22, v137, s71, 48
	v_lshlrev_b64 v[20:21], 10, v[20:21]
	v_ashrrev_i32_e32 v23, 31, v22
	v_lshl_add_u64 v[20:21], v[154:155], 0, v[20:21]
	v_lshl_add_u64 v[22:23], v[22:23], 1, v[156:157]
	global_load_dwordx4 v[24:27], v[20:21], off
	s_nop 0
	global_load_dwordx4 v[20:23], v[22:23], off
	s_nop 0
	global_load_dwordx4 v[56:59], v[158:159], off offset:-112
	global_load_dwordx4 v[60:63], v[158:159], off offset:-128
	global_load_dwordx4 v[64:67], v[158:159], off offset:16
	global_load_dwordx4 v[68:71], v[158:159], off

.LBB0_883:
	v_xor_b32_e32 v220, 0x8000, v220
	v_xor_b32_e32 v221, 0x8000, v221
	v_xor_b32_e32 v222, 0x8000, v222
	v_xor_b32_e32 v223, 0x8000, v223
	s_mov_b64 s[4:5], 0x100
	s_add_i32 s71, s71, 64
	v_lshl_add_u64 v[158:159], v[158:159], 0, s[4:5]
	s_and_b64 vcc, exec, s[54:55]
	s_cbranch_vccnz .LBB0_885
	s_waitcnt vmcnt(1)
	v_mov_b64_e32 v[74:75], v[66:67]
	s_waitcnt vmcnt(0)
	v_mov_b64_e32 v[82:83], v[70:71]
	v_mov_b64_e32 v[78:79], v[58:59]
	v_mov_b64_e32 v[86:87], v[62:63]
	v_mov_b64_e32 v[72:73], v[64:65]
	v_mov_b64_e32 v[80:81], v[68:69]
	v_mov_b64_e32 v[76:77], v[56:57]
	v_mov_b64_e32 v[84:85], v[60:61]
	s_branch .LBB0_871
